# as v45 plus block-boundary wait relaxation: attention unit end (MLA and windowed GQA) no longer drains the O stores (vmcnt(0) dropped, lgkmcnt(0) kept) before the LDS-only barrier
# baseline (speedup 1.0000x reference)
; #define LAS __attribute__((address_space(3)))
; __device__ __forceinline__ unsigned cvt_pk_bf16(float lo, float hi) { unsigned r; asm volatile("v_cvt_pk_bf16_f32 %0, %1, %2" : "=v"(r) : "v"(lo), "v"(hi)); return r; }
; __device__ __forceinline__ int crow(int r, int hi) { return (r & 3) + 8 * (r >> 2) + 4 * hi; }
; __device__ __forceinline__ float halfsum(float m) { auto rr = __builtin_amdgcn_permlane32_swap(__float_as_uint(m), __float_as_uint(m), false, false); return __uint_as_float(rr[0]) + __uint_as_float(rr[1]); }
; template <int MODE> __device__ __forceinline__ void attn_unit(const Unit& a, char* shm) {
;     ...
;     l_reg = halfsum(l_reg);
;     if (hi == 0) wsf[32 + r32] = l_reg;
;     float rli[16];
; #pragma unroll
;     for (int r = 0; r < 16; ++r) rli[r] = __builtin_amdgcn_rcpf(wsf[32 + crow(r, hi)]);
;     { LAS bf16_t* stg = (LAS bf16_t*)(shm3 + LDS_OST) + wid * 2048;
; #pragma unroll
;       for (int r = 0; r < 16; ++r) { const int orow = crow(r, hi);
; #pragma unroll
;           for (int d0 = 0; d0 < 2; ++d0) stg[orow * 64 + d0 * 32 + r32] = (bf16_t)(cvt_pk_bf16(o[d0][r] * rli[r], 0.f) & 0xffffu); }
;       bf16_t* Ow = a.O + (long)(wid * 32) * a.ldo;
; #pragma unroll
;       for (int i = 0; i < 4; ++i) { const int row = i * 8 + (lane >> 3), ch = lane & 7; const u32x4 v = *(const LAS u32x4*)(stg + row * 64 + ch * 8); *(u32x4*)(Ow + (long)row * a.ldo + ch * 8) = v; } }
;     asm volatile("s_waitcnt vmcnt(0) lgkmcnt(0)\n\ts_barrier" ::: "memory");
.LBB0_1321:
	s_or_b64 exec, exec, s[44:45]
	v_lshl_add_u32 v40, v161, 4, s25
	ds_read_b128 v[32:35], v40 offset:49280
	ds_read_b128 v[36:39], v40 offset:49312
	s_lshl_b32 s0, s24, 12
	s_add_i32 s12, s0, 0
	v_lshlrev_b32_e32 v49, 1, v160
	s_waitcnt lgkmcnt(1)
	v_rcp_f32_e32 v41, v32
	v_rcp_f32_e32 v42, v33
	v_rcp_f32_e32 v43, v34
	v_rcp_f32_e32 v44, v35
	s_waitcnt lgkmcnt(0)
	v_rcp_f32_e32 v45, v36
	ds_read_b128 v[32:35], v40 offset:49344
	v_rcp_f32_e32 v46, v37
	v_rcp_f32_e32 v47, v38
	v_rcp_f32_e32 v48, v39
	ds_read_b128 v[36:39], v40 offset:49376
	v_lshlrev_b32_e32 v40, 9, v161
	v_add3_u32 v40, s12, v40, v49
	v_mul_f32_e32 v16, v16, v41
	v_mul_f32_e32 v0, v0, v41
	v_cvt_pk_bf16_f32 v16, v16, v81
	ds_write_b16 v40, v16 offset:51200
	v_cvt_pk_bf16_f32 v0, v0, v81
	ds_write_b16 v40, v0 offset:51264
	v_mul_f32_e32 v0, v17, v42
	v_cvt_pk_bf16_f32 v0, v0, v81
	ds_write_b16 v40, v0 offset:51328
	v_mul_f32_e32 v0, v1, v42
	v_cvt_pk_bf16_f32 v0, v0, v81
	ds_write_b16 v40, v0 offset:51392
	v_mul_f32_e32 v0, v18, v43
	v_cvt_pk_bf16_f32 v0, v0, v81
	ds_write_b16 v40, v0 offset:51456
	v_mul_f32_e32 v0, v2, v43
	v_cvt_pk_bf16_f32 v0, v0, v81
	ds_write_b16 v40, v0 offset:51520
	v_mul_f32_e32 v0, v19, v44
	v_cvt_pk_bf16_f32 v0, v0, v81
	ds_write_b16 v40, v0 offset:51584
	v_mul_f32_e32 v0, v3, v44
	v_cvt_pk_bf16_f32 v0, v0, v81
	ds_write_b16 v40, v0 offset:51648
	v_mul_f32_e32 v0, v20, v45
	v_cvt_pk_bf16_f32 v0, v0, v81
	ds_write_b16 v40, v0 offset:52224
	v_mul_f32_e32 v0, v4, v45
	v_cvt_pk_bf16_f32 v0, v0, v81
	ds_write_b16 v40, v0 offset:52288
	v_mul_f32_e32 v0, v21, v46
	v_cvt_pk_bf16_f32 v0, v0, v81
	ds_write_b16 v40, v0 offset:52352
	v_mul_f32_e32 v0, v5, v46
	v_cvt_pk_bf16_f32 v0, v0, v81
	ds_write_b16 v40, v0 offset:52416
	v_mul_f32_e32 v0, v22, v47
	v_cvt_pk_bf16_f32 v0, v0, v81
	ds_write_b16 v40, v0 offset:52480
	v_mul_f32_e32 v0, v6, v47
	v_cvt_pk_bf16_f32 v0, v0, v81
	s_waitcnt lgkmcnt(14)
	v_rcp_f32_e32 v32, v32
	ds_write_b16 v40, v0 offset:52544
	v_mul_f32_e32 v0, v23, v48
	v_cvt_pk_bf16_f32 v0, v0, v81
	ds_write_b16 v40, v0 offset:52608
	v_mul_f32_e32 v0, v7, v48
	v_cvt_pk_bf16_f32 v0, v0, v81
	v_rcp_f32_e32 v33, v33
	ds_write_b16 v40, v0 offset:52672
	v_mul_f32_e32 v0, v24, v32
	v_cvt_pk_bf16_f32 v0, v0, v81
	ds_write_b16 v40, v0 offset:53248
	v_mul_f32_e32 v0, v8, v32
	v_cvt_pk_bf16_f32 v0, v0, v81
	v_rcp_f32_e32 v34, v34
	ds_write_b16 v40, v0 offset:53312
	v_mul_f32_e32 v0, v25, v33
	v_cvt_pk_bf16_f32 v0, v0, v81
	ds_write_b16 v40, v0 offset:53376
	v_mul_f32_e32 v0, v9, v33
	v_cvt_pk_bf16_f32 v0, v0, v81
	v_rcp_f32_e32 v35, v35
	ds_write_b16 v40, v0 offset:53440
	v_mul_f32_e32 v0, v26, v34
	v_cvt_pk_bf16_f32 v0, v0, v81
	ds_write_b16 v40, v0 offset:53504
	v_mul_f32_e32 v0, v10, v34
	v_cvt_pk_bf16_f32 v0, v0, v81
	s_waitcnt lgkmcnt(14)
	v_rcp_f32_e32 v36, v36
	ds_write_b16 v40, v0 offset:53568
	v_mul_f32_e32 v0, v27, v35
	v_cvt_pk_bf16_f32 v0, v0, v81
	ds_write_b16 v40, v0 offset:53632
	v_mul_f32_e32 v0, v11, v35
	v_cvt_pk_bf16_f32 v0, v0, v81
	v_rcp_f32_e32 v37, v37
	ds_write_b16 v40, v0 offset:53696
	v_mul_f32_e32 v0, v28, v36
	v_cvt_pk_bf16_f32 v0, v0, v81
	ds_write_b16 v40, v0 offset:54272
	v_mul_f32_e32 v0, v12, v36
	v_cvt_pk_bf16_f32 v0, v0, v81
	v_rcp_f32_e32 v38, v38
	ds_write_b16 v40, v0 offset:54336
	v_mul_f32_e32 v0, v29, v37
	v_cvt_pk_bf16_f32 v0, v0, v81
	ds_write_b16 v40, v0 offset:54400
	v_mul_f32_e32 v0, v13, v37
	v_cvt_pk_bf16_f32 v0, v0, v81
	v_rcp_f32_e32 v39, v39
	ds_write_b16 v40, v0 offset:54464
	v_mul_f32_e32 v0, v30, v38
	v_cvt_pk_bf16_f32 v0, v0, v81
	ds_write_b16 v40, v0 offset:54528
	v_mul_f32_e32 v0, v14, v38
	v_cvt_pk_bf16_f32 v0, v0, v81
	ds_write_b16 v40, v0 offset:54592
	v_mul_f32_e32 v0, v31, v39
	v_cvt_pk_bf16_f32 v0, v0, v81
	ds_write_b16 v40, v0 offset:54656
	v_mul_f32_e32 v0, v15, v39
	v_cvt_pk_bf16_f32 v0, v0, v81
	ds_write_b16 v40, v0 offset:54720
	v_lshrrev_b32_e32 v6, 3, v158
	v_lshlrev_b32_e32 v0, 1, v159
	s_mul_hi_i32 s1, s23, 0x1600
	s_mulk_i32 s23, 0x1600
	v_and_b32_e32 v80, 0x70, v0
	v_lshlrev_b32_e32 v0, 7, v6
	s_add_u32 s0, s2, s23
	v_add3_u32 v12, s12, v80, v0
	s_addc_u32 s1, s3, s1
	ds_read_b128 v[0:3], v12 offset:51200
	v_mul_u32_u24_e32 v6, 0xb00, v6
	v_lshl_add_u64 v[4:5], s[0:1], 0, v[80:81]
	v_lshlrev_b32_e32 v80, 1, v6
	v_lshl_add_u64 v[8:9], v[4:5], 0, v[80:81]
	ds_read_b128 v[4:7], v12 offset:52224
	s_waitcnt lgkmcnt(1)
	global_store_dwordx4 v[8:9], v[0:3], off offset:1024
	s_add_i32 s22, s22, s92
	s_cmpk_gt_i32 s22, 0x3ff
	v_add_co_u32_e32 v0, vcc, 0xb000, v8
	s_nop 1
	v_addc_co_u32_e32 v1, vcc, 0, v9, vcc
	s_waitcnt lgkmcnt(0)
	global_store_dwordx4 v[0:1], v[4:7], off offset:1024
	ds_read_b128 v[0:3], v12 offset:53248
	ds_read_b128 v[4:7], v12 offset:54272
	v_add_co_u32_e32 v10, vcc, 0x16000, v8
	s_nop 1
	v_addc_co_u32_e32 v11, vcc, 0, v9, vcc
	s_waitcnt lgkmcnt(1)
	global_store_dwordx4 v[10:11], v[0:3], off offset:1024
	s_nop 1
	v_add_co_u32_e32 v0, vcc, 0x21000, v8
	s_nop 1
	v_addc_co_u32_e32 v1, vcc, 0, v9, vcc
	s_waitcnt lgkmcnt(0)
	global_store_dwordx4 v[0:1], v[4:7], off offset:1024
	s_waitcnt lgkmcnt(0)
	s_barrier
	s_cbranch_scc1 .LBB0_1316

; #define LAS __attribute__((address_space(3)))
; __device__ __forceinline__ unsigned cvt_pk_bf16(float lo, float hi) { unsigned r; asm volatile("v_cvt_pk_bf16_f32 %0, %1, %2" : "=v"(r) : "v"(lo), "v"(hi)); return r; }
; __device__ __forceinline__ int crow(int r, int hi) { return (r & 3) + 8 * (r >> 2) + 4 * hi; }
; __device__ __forceinline__ float halfsum(float m) { auto rr = __builtin_amdgcn_permlane32_swap(__float_as_uint(m), __float_as_uint(m), false, false); return __uint_as_float(rr[0]) + __uint_as_float(rr[1]); }
; template <int MODE> __device__ __forceinline__ void attn_unit(const Unit& a, char* shm) {
;     ...
;     l_reg = halfsum(l_reg);
;     if (hi == 0) wsf[32 + r32] = l_reg;
;     float rli[16];
; #pragma unroll
;     for (int r = 0; r < 16; ++r) rli[r] = __builtin_amdgcn_rcpf(wsf[32 + crow(r, hi)]);
;     { LAS bf16_t* stg = (LAS bf16_t*)(shm3 + LDS_OST) + wid * 2048;
; #pragma unroll
;       for (int r = 0; r < 16; ++r) { const int orow = crow(r, hi);
; #pragma unroll
;           for (int d0 = 0; d0 < 2; ++d0) stg[orow * 64 + d0 * 32 + r32] = (bf16_t)(cvt_pk_bf16(o[d0][r] * rli[r], 0.f) & 0xffffu); }
;       bf16_t* Ow = a.O + (long)(wid * 32) * a.ldo;
; #pragma unroll
;       for (int i = 0; i < 4; ++i) { const int row = i * 8 + (lane >> 3), ch = lane & 7; const u32x4 v = *(const LAS u32x4*)(stg + row * 64 + ch * 8); *(u32x4*)(Ow + (long)row * a.ldo + ch * 8) = v; } }
;     asm volatile("s_waitcnt vmcnt(0) lgkmcnt(0)\n\ts_barrier" ::: "memory");
.LBB0_1898:
	s_or_b64 exec, exec, s[2:3]
	v_add_u32_e32 v40, s49, v80
	ds_read_b128 v[32:35], v40 offset:49280
	ds_read_b128 v[36:39], v40 offset:49312
	s_mulk_i32 s28, 0x1600
	s_mul_hi_u32 s0, s27, 0x1600
	s_add_i32 s0, s0, s28
	s_mulk_i32 s27, 0x1600
	s_add_u32 s1, s36, s27
	s_waitcnt lgkmcnt(1)
	v_rcp_f32_e32 v41, v32
	s_addc_u32 s0, s37, s0
	s_lshl_b32 s2, s26, 7
	s_add_u32 s1, s1, s2
	s_addc_u32 s2, s0, 0
	s_lshl_b32 s0, s25, 12
	v_rcp_f32_e32 v42, v33
	v_rcp_f32_e32 v43, v34
	v_rcp_f32_e32 v44, v35
	s_waitcnt lgkmcnt(0)
	v_rcp_f32_e32 v45, v36
	ds_read_b128 v[32:35], v40 offset:49344
	v_rcp_f32_e32 v46, v37
	v_rcp_f32_e32 v47, v38
	v_rcp_f32_e32 v48, v39
	ds_read_b128 v[36:39], v40 offset:49376
	s_add_i32 s3, s0, 0
	v_lshlrev_b32_e32 v40, 9, v145
	v_lshlrev_b32_e32 v49, 1, v144
	v_mul_f32_e32 v0, v0, v41
	v_add3_u32 v40, s3, v40, v49
	v_cvt_pk_bf16_f32 v0, v0, v81
	ds_write_b16 v40, v0 offset:51200
	v_mul_f32_e32 v0, v16, v41
	v_cvt_pk_bf16_f32 v0, v0, v81
	ds_write_b16 v40, v0 offset:51264
	v_mul_f32_e32 v0, v1, v42
	v_cvt_pk_bf16_f32 v0, v0, v81
	ds_write_b16 v40, v0 offset:51328
	v_mul_f32_e32 v0, v17, v42
	v_cvt_pk_bf16_f32 v0, v0, v81
	ds_write_b16 v40, v0 offset:51392
	v_mul_f32_e32 v0, v2, v43
	v_cvt_pk_bf16_f32 v0, v0, v81
	ds_write_b16 v40, v0 offset:51456
	v_mul_f32_e32 v0, v18, v43
	v_cvt_pk_bf16_f32 v0, v0, v81
	ds_write_b16 v40, v0 offset:51520
	v_mul_f32_e32 v0, v3, v44
	v_cvt_pk_bf16_f32 v0, v0, v81
	ds_write_b16 v40, v0 offset:51584
	v_mul_f32_e32 v0, v19, v44
	v_cvt_pk_bf16_f32 v0, v0, v81
	ds_write_b16 v40, v0 offset:51648
	v_mul_f32_e32 v0, v4, v45
	v_cvt_pk_bf16_f32 v0, v0, v81
	ds_write_b16 v40, v0 offset:52224
	v_mul_f32_e32 v0, v20, v45
	v_cvt_pk_bf16_f32 v0, v0, v81
	ds_write_b16 v40, v0 offset:52288
	v_mul_f32_e32 v0, v5, v46
	v_cvt_pk_bf16_f32 v0, v0, v81
	ds_write_b16 v40, v0 offset:52352
	v_mul_f32_e32 v0, v21, v46
	v_cvt_pk_bf16_f32 v0, v0, v81
	ds_write_b16 v40, v0 offset:52416
	v_mul_f32_e32 v0, v6, v47
	v_cvt_pk_bf16_f32 v0, v0, v81
	ds_write_b16 v40, v0 offset:52480
	v_mul_f32_e32 v0, v22, v47
	v_cvt_pk_bf16_f32 v0, v0, v81
	s_waitcnt lgkmcnt(14)
	v_rcp_f32_e32 v32, v32
	ds_write_b16 v40, v0 offset:52544
	v_mul_f32_e32 v0, v7, v48
	v_cvt_pk_bf16_f32 v0, v0, v81
	ds_write_b16 v40, v0 offset:52608
	v_mul_f32_e32 v0, v23, v48
	v_cvt_pk_bf16_f32 v0, v0, v81
	v_rcp_f32_e32 v33, v33
	ds_write_b16 v40, v0 offset:52672
	v_mul_f32_e32 v0, v8, v32
	v_cvt_pk_bf16_f32 v0, v0, v81
	ds_write_b16 v40, v0 offset:53248
	v_mul_f32_e32 v0, v24, v32
	v_cvt_pk_bf16_f32 v0, v0, v81
	v_rcp_f32_e32 v34, v34
	ds_write_b16 v40, v0 offset:53312
	v_mul_f32_e32 v0, v9, v33
	v_cvt_pk_bf16_f32 v0, v0, v81
	ds_write_b16 v40, v0 offset:53376
	v_mul_f32_e32 v0, v25, v33
	v_cvt_pk_bf16_f32 v0, v0, v81
	v_rcp_f32_e32 v35, v35
	ds_write_b16 v40, v0 offset:53440
	v_mul_f32_e32 v0, v10, v34
	v_cvt_pk_bf16_f32 v0, v0, v81
	ds_write_b16 v40, v0 offset:53504
	v_mul_f32_e32 v0, v26, v34
	v_cvt_pk_bf16_f32 v0, v0, v81
	s_waitcnt lgkmcnt(14)
	v_rcp_f32_e32 v36, v36
	ds_write_b16 v40, v0 offset:53568
	v_mul_f32_e32 v0, v11, v35
	v_cvt_pk_bf16_f32 v0, v0, v81
	ds_write_b16 v40, v0 offset:53632
	v_mul_f32_e32 v0, v27, v35
	v_cvt_pk_bf16_f32 v0, v0, v81
	v_rcp_f32_e32 v37, v37
	ds_write_b16 v40, v0 offset:53696
	v_mul_f32_e32 v0, v12, v36
	v_cvt_pk_bf16_f32 v0, v0, v81
	ds_write_b16 v40, v0 offset:54272
	v_mul_f32_e32 v0, v28, v36
	v_cvt_pk_bf16_f32 v0, v0, v81
	v_rcp_f32_e32 v38, v38
	ds_write_b16 v40, v0 offset:54336
	v_mul_f32_e32 v0, v13, v37
	v_cvt_pk_bf16_f32 v0, v0, v81
	ds_write_b16 v40, v0 offset:54400
	v_mul_f32_e32 v0, v29, v37
	v_cvt_pk_bf16_f32 v0, v0, v81
	v_rcp_f32_e32 v39, v39
	ds_write_b16 v40, v0 offset:54464
	v_mul_f32_e32 v0, v14, v38
	v_cvt_pk_bf16_f32 v0, v0, v81
	ds_write_b16 v40, v0 offset:54528
	v_mul_f32_e32 v0, v30, v38
	v_cvt_pk_bf16_f32 v0, v0, v81
	ds_write_b16 v40, v0 offset:54592
	v_mul_f32_e32 v0, v15, v39
	v_cvt_pk_bf16_f32 v0, v0, v81
	ds_write_b16 v40, v0 offset:54656
	v_mul_f32_e32 v0, v31, v39
	v_cvt_pk_bf16_f32 v0, v0, v81
	ds_write_b16 v40, v0 offset:54720
	v_lshrrev_b32_e32 v6, 3, v142
	v_lshlrev_b32_e32 v0, 1, v143
	s_mul_hi_i32 s12, s24, 0x1600
	s_mulk_i32 s24, 0x1600
	v_and_b32_e32 v80, 0x70, v0
	v_lshlrev_b32_e32 v0, 7, v6
	s_add_u32 s0, s1, s24
	v_add3_u32 v12, s3, v80, v0
	s_addc_u32 s1, s2, s12
	ds_read_b128 v[0:3], v12 offset:51200
	v_mul_u32_u24_e32 v6, 0xb00, v6
	v_lshl_add_u64 v[4:5], s[0:1], 0, v[80:81]
	v_lshlrev_b32_e32 v80, 1, v6
	v_lshl_add_u64 v[8:9], v[4:5], 0, v[80:81]
	ds_read_b128 v[4:7], v12 offset:52224
	s_waitcnt lgkmcnt(1)
	global_store_dwordx4 v[8:9], v[0:3], off offset:1024
	s_add_i32 s22, s22, s92
	s_cmpk_gt_i32 s22, 0x3ff
	v_add_co_u32_e32 v0, vcc, 0xb000, v8
	s_nop 1
	v_addc_co_u32_e32 v1, vcc, 0, v9, vcc
	s_waitcnt lgkmcnt(0)
	global_store_dwordx4 v[0:1], v[4:7], off offset:1024
	ds_read_b128 v[0:3], v12 offset:53248
	ds_read_b128 v[4:7], v12 offset:54272
	v_add_co_u32_e32 v10, vcc, 0x16000, v8
	s_nop 1
	v_addc_co_u32_e32 v11, vcc, 0, v9, vcc
	s_waitcnt lgkmcnt(1)
	global_store_dwordx4 v[10:11], v[0:3], off offset:1024
	s_nop 1
	v_add_co_u32_e32 v0, vcc, 0x21000, v8
	s_nop 1
	v_addc_co_u32_e32 v1, vcc, 0, v9, vcc
	s_waitcnt lgkmcnt(0)
	global_store_dwordx4 v[0:1], v[4:7], off offset:1024
	s_waitcnt lgkmcnt(0)
	s_barrier
	s_cbranch_scc1 .LBB0_1893
